# indexer score loop: separate masked copy for a wave's last tile, unmasked running max/min for earlier (fully causal) tiles
# speedup vs baseline: 1.0041x; 1.0041x over previous
; __device__ __forceinline__ void indexer_phase(const bf16_t* PJ, float* rk, unsigned short* SEL, LAS unsigned char* lds) {
;     ...
;             while (kt < nkt) {
;                 const int kn = kt + NWAVE;
;                 if (kn < nkt) {
; #pragma unroll
;                     for (int kk = 0; kk < 4; ++kk) bnxt[kk] = *(const bf16x8*)(kbase + (size_t)(32 * kn) * PROJ_LD + kk * 16);
;                 }
;                 const int key = 32 * kt + r32;
; #pragma unroll
;                 for (int rt = 0; rt < 2; ++rt) {
;                     f32x16 acc = f32x16{};
; #pragma unroll
;                     for (int kk = 0; kk < 4; ++kk) acc = __builtin_amdgcn_mfma_f32_32x32x16_bf16(af[rt][kk], bcur[kk], acc, 0, 0, 0);
.Lidx_loopA:
	s_add_i32 s1, s1, 8
	s_cmp_ge_i32 s1, s0
	s_cbranch_scc1 .Lidx_last
	s_add_i32 s3, s6, 0x100
	s_add_i32 s32, s1, 8
	s_cmp_lt_i32 s32, s0
	s_cbranch_scc0 .Lidx_nofarA
	s_add_i32 s32, s6, 0x200
	v_mad_i64_i32 v[0:1], s[26:27], s32, v177, v[216:217]
	s_add_i32 s32, s32, 16
	v_mad_i64_i32 v[220:221], s[26:27], s32, v177, v[216:217]
	global_load_dwordx4 v[228:231], v[0:1], off
	global_load_dwordx4 v[232:235], v[220:221], off
	global_load_dwordx4 v[236:239], v[0:1], off offset:64
	global_load_dwordx4 v[240:243], v[220:221], off offset:64
.Lidx_nofarA:
	s_waitcnt lgkmcnt(0)
	v_mfma_f32_32x32x16_bf16 v[0:15], v[72:75], v[244:247], 0
	v_mfma_f32_32x32x16_bf16 v[0:15], v[64:67], v[104:107], v[0:15]
	v_mfma_f32_32x32x16_bf16 v[0:15], v[68:71], v[100:103], v[0:15]
	v_mfma_f32_32x32x16_bf16 v[0:15], v[76:79], v[96:99], v[0:15]
	v_mfma_f32_32x32x16_bf16 v[16:31], v[88:91], v[244:247], 0
	v_mfma_f32_32x32x16_bf16 v[16:31], v[80:83], v[104:107], v[16:31]
	v_mfma_f32_32x32x16_bf16 v[16:31], v[84:87], v[100:103], v[16:31]
	v_mfma_f32_32x32x16_bf16 v[16:31], v[92:95], v[96:99], v[16:31]
	s_add_i32 s32, s1, 8
	s_cmp_lt_i32 s32, s0
	s_cbranch_scc1 .Lidx_w4A
	s_waitcnt vmcnt(0)
	s_branch .Lidx_trA

; #define LAS __attribute__((address_space(3)))
; __device__ __forceinline__ void indexer_phase(const bf16_t* PJ, float* rk, unsigned short* SEL, LAS unsigned char* lds) {
;     ...
;                 const int key = 32 * kt + r32;
; #pragma unroll
;                 for (int rt = 0; rt < 2; ++rt) {
;                     f32x16 acc = f32x16{};
; #pragma unroll
;                     for (int kk = 0; kk < 4; ++kk) acc = __builtin_amdgcn_mfma_f32_32x32x16_bf16(af[rt][kk], bcur[kk], acc, 0, 0, 0);
; #pragma unroll
;                     for (int qq = 0; qq < 2; ++qq) { float s = 0.f;
; #pragma unroll
;                         for (int e = 0; e < 8; ++e) s += wq[rt][qq][e] * fmaxf(acc[8 * qq + e], 0.f);
;                         ((LAS float*)lds)[(4 * rt + 2 * hi + qq) * 4096 + key] = s;
;                         const bool ok = key <= t0 + 4 * rt + 2 * hi + qq;
;                         rmax[rt][qq] = fmaxf(rmax[rt][qq], ok ? s : -INFINITY); rmin[rt][qq] = fminf(rmin[rt][qq], ok ? s : INFINITY); }
;                 }
; #pragma unroll
;                 for (int kk = 0; kk < 4; ++kk) bcur[kk] = bnxt[kk];
;                 kt = kn;
.Lidx_trA:
	ds_write_b128 v222, v[52:55]
	ds_write_b128 v222, v[56:59] offset:1024
	s_nop 3
	v_max_f32_e32 v0, 0, v0
	v_max_f32_e32 v1, 0, v1
	v_pk_mul_f32 v[0:1], v[126:127], v[0:1] op_sel:[1,0] op_sel_hi:[0,1]
	v_max_f32_e32 v2, 0, v2
	v_max_f32_e32 v3, 0, v3
	v_pk_mul_f32 v[2:3], v[128:129], v[2:3] op_sel:[1,0] op_sel_hi:[0,1]
	v_max_f32_e32 v4, 0, v4
	v_max_f32_e32 v5, 0, v5
	v_pk_mul_f32 v[4:5], v[130:131], v[4:5] op_sel:[1,0] op_sel_hi:[0,1]
	v_max_f32_e32 v6, 0, v6
	v_max_f32_e32 v7, 0, v7
	v_pk_mul_f32 v[6:7], v[132:133], v[6:7] op_sel:[1,0] op_sel_hi:[0,1]
	v_add_f32_e32 v0, 0, v0
	v_max_f32_e32 v8, 0, v8
	v_add_f32_e32 v0, v1, v0
	v_max_f32_e32 v9, 0, v9
	v_add_f32_e32 v0, v2, v0
	v_pk_mul_f32 v[8:9], v[134:135], v[8:9] op_sel:[1,0] op_sel_hi:[0,1]
	v_add_f32_e32 v0, v3, v0
	v_max_f32_e32 v10, 0, v10
	v_add_f32_e32 v0, v4, v0
	v_max_f32_e32 v11, 0, v11
	v_add_f32_e32 v0, v5, v0
	v_pk_mul_f32 v[10:11], v[136:137], v[10:11] op_sel:[1,0] op_sel_hi:[0,1]
	v_add_f32_e32 v0, v6, v0
	v_max_f32_e32 v12, 0, v12
	v_add_f32_e32 v0, v7, v0
	v_max_f32_e32 v13, 0, v13
	v_pk_mul_f32 v[12:13], v[138:139], v[12:13] op_sel:[1,0] op_sel_hi:[0,1]
	v_max_f32_e32 v14, 0, v14
	v_max_f32_e32 v15, 0, v15
	v_pk_mul_f32 v[14:15], v[140:141], v[14:15] op_sel:[1,0] op_sel_hi:[0,1]
	s_waitcnt lgkmcnt(0)
	ds_read_b128 v[244:247], v223
	ds_read_b128 v[104:107], v224
	v_add_f32_e32 v8, 0, v8
	v_add_f32_e32 v8, v9, v8
	v_add_f32_e32 v8, v10, v8
	v_add_f32_e32 v8, v11, v8
	v_max_f32_e32 v189, v189, v0
	v_min_f32_e32 v188, v188, v0
	v_add_f32_e32 v8, v12, v8
	v_add_f32_e32 v8, v13, v8
	v_add_f32_e32 v8, v14, v8
	v_add_f32_e32 v8, v15, v8
	s_waitcnt lgkmcnt(0)
	ds_write_b128 v222, v[60:63]
	ds_write_b128 v222, v[48:51] offset:1024
	ds_write2st64_b32 v196, v0, v8 offset1:64
	v_max_f32_e32 v16, 0, v16
	v_max_f32_e32 v17, 0, v17
	v_pk_mul_f32 v[16:17], v[142:143], v[16:17] op_sel:[1,0] op_sel_hi:[0,1]
	v_max_f32_e32 v187, v187, v8
	v_min_f32_e32 v186, v186, v8
	v_max_f32_e32 v18, 0, v18
	v_max_f32_e32 v19, 0, v19
	v_pk_mul_f32 v[18:19], v[144:145], v[18:19] op_sel:[1,0] op_sel_hi:[0,1]
	v_max_f32_e32 v20, 0, v20
	v_max_f32_e32 v21, 0, v21
	v_pk_mul_f32 v[20:21], v[146:147], v[20:21] op_sel:[1,0] op_sel_hi:[0,1]
	v_max_f32_e32 v22, 0, v22
	v_max_f32_e32 v23, 0, v23
	v_pk_mul_f32 v[22:23], v[148:149], v[22:23] op_sel:[1,0] op_sel_hi:[0,1]
	v_add_f32_e32 v16, 0, v16
	v_max_f32_e32 v24, 0, v24
	v_add_f32_e32 v16, v17, v16
	v_max_f32_e32 v25, 0, v25
	v_add_f32_e32 v16, v18, v16
	v_pk_mul_f32 v[24:25], v[150:151], v[24:25] op_sel:[1,0] op_sel_hi:[0,1]
	v_add_f32_e32 v16, v19, v16
	v_max_f32_e32 v26, 0, v26
	v_add_f32_e32 v16, v20, v16
	v_max_f32_e32 v27, 0, v27
	v_add_f32_e32 v16, v21, v16
	v_pk_mul_f32 v[26:27], v[152:153], v[26:27] op_sel:[1,0] op_sel_hi:[0,1]
	v_add_f32_e32 v16, v22, v16
	v_max_f32_e32 v28, 0, v28
	v_add_f32_e32 v16, v23, v16
	v_max_f32_e32 v29, 0, v29
	v_pk_mul_f32 v[28:29], v[154:155], v[28:29] op_sel:[1,0] op_sel_hi:[0,1]
	v_max_f32_e32 v30, 0, v30
	v_max_f32_e32 v31, 0, v31
	v_pk_mul_f32 v[30:31], v[156:157], v[30:31] op_sel:[1,0] op_sel_hi:[0,1]
	v_add_u32_e32 v3, 0x10000, v196
	s_waitcnt lgkmcnt(0)
	ds_read_b128 v[100:103], v223
	ds_read_b128 v[96:99], v224
	v_add_f32_e32 v24, 0, v24
	v_add_f32_e32 v24, v25, v24
	v_add_f32_e32 v24, v26, v24
	v_add_f32_e32 v24, v27, v24
	ds_write_b32 v3, v16
	v_max_f32_e32 v185, v185, v16
	v_min_f32_e32 v184, v184, v16
	v_add_f32_e32 v24, v28, v24
	v_add_f32_e32 v24, v29, v24
	v_add_f32_e32 v24, v30, v24
	v_add_f32_e32 v24, v31, v24
	v_add_u32_e32 v3, 0x14000, v196
	v_add_u32_e32 v196, 0x400, v196
	s_nop 0
	ds_write_b32 v3, v24
	v_max_f32_e32 v183, v183, v24
	v_min_f32_e32 v123, v123, v24
	s_mov_b32 s6, s3
.Lidx_loopB:
	s_add_i32 s1, s1, 8
	s_cmp_ge_i32 s1, s0
	s_cbranch_scc1 .Lidx_last
	s_add_i32 s3, s6, 0x100
	s_add_i32 s32, s1, 8
	s_cmp_lt_i32 s32, s0
	s_cbranch_scc0 .Lidx_nofarB
	s_add_i32 s32, s6, 0x200
	v_mad_i64_i32 v[0:1], s[26:27], s32, v177, v[216:217]
	s_add_i32 s32, s32, 16
	v_mad_i64_i32 v[220:221], s[26:27], s32, v177, v[216:217]
	global_load_dwordx4 v[52:55], v[0:1], off
	global_load_dwordx4 v[56:59], v[220:221], off
	global_load_dwordx4 v[60:63], v[0:1], off offset:64
	global_load_dwordx4 v[48:51], v[220:221], off offset:64

; #define LAS __attribute__((address_space(3)))
; __device__ __forceinline__ void indexer_phase(const bf16_t* PJ, float* rk, unsigned short* SEL, LAS unsigned char* lds) {
;     ...
;                 const int key = 32 * kt + r32;
; #pragma unroll
;                 for (int rt = 0; rt < 2; ++rt) {
;                     f32x16 acc = f32x16{};
; #pragma unroll
;                     for (int kk = 0; kk < 4; ++kk) acc = __builtin_amdgcn_mfma_f32_32x32x16_bf16(af[rt][kk], bcur[kk], acc, 0, 0, 0);
; #pragma unroll
;                     for (int qq = 0; qq < 2; ++qq) { float s = 0.f;
; #pragma unroll
;                         for (int e = 0; e < 8; ++e) s += wq[rt][qq][e] * fmaxf(acc[8 * qq + e], 0.f);
;                         ((LAS float*)lds)[(4 * rt + 2 * hi + qq) * 4096 + key] = s;
;                         const bool ok = key <= t0 + 4 * rt + 2 * hi + qq;
;                         rmax[rt][qq] = fmaxf(rmax[rt][qq], ok ? s : -INFINITY); rmin[rt][qq] = fminf(rmin[rt][qq], ok ? s : INFINITY); }
;                 }
; #pragma unroll
;                 for (int kk = 0; kk < 4; ++kk) bcur[kk] = bnxt[kk];
;                 kt = kn;
.Lidx_trB:
	ds_write_b128 v222, v[228:231]
	ds_write_b128 v222, v[232:235] offset:1024
	s_nop 3
	v_max_f32_e32 v0, 0, v0
	v_max_f32_e32 v1, 0, v1
	v_pk_mul_f32 v[0:1], v[126:127], v[0:1] op_sel:[1,0] op_sel_hi:[0,1]
	v_max_f32_e32 v2, 0, v2
	v_max_f32_e32 v3, 0, v3
	v_pk_mul_f32 v[2:3], v[128:129], v[2:3] op_sel:[1,0] op_sel_hi:[0,1]
	v_max_f32_e32 v4, 0, v4
	v_max_f32_e32 v5, 0, v5
	v_pk_mul_f32 v[4:5], v[130:131], v[4:5] op_sel:[1,0] op_sel_hi:[0,1]
	v_max_f32_e32 v6, 0, v6
	v_max_f32_e32 v7, 0, v7
	v_pk_mul_f32 v[6:7], v[132:133], v[6:7] op_sel:[1,0] op_sel_hi:[0,1]
	v_add_f32_e32 v0, 0, v0
	v_max_f32_e32 v8, 0, v8
	v_add_f32_e32 v0, v1, v0
	v_max_f32_e32 v9, 0, v9
	v_add_f32_e32 v0, v2, v0
	v_pk_mul_f32 v[8:9], v[134:135], v[8:9] op_sel:[1,0] op_sel_hi:[0,1]
	v_add_f32_e32 v0, v3, v0
	v_max_f32_e32 v10, 0, v10
	v_add_f32_e32 v0, v4, v0
	v_max_f32_e32 v11, 0, v11
	v_add_f32_e32 v0, v5, v0
	v_pk_mul_f32 v[10:11], v[136:137], v[10:11] op_sel:[1,0] op_sel_hi:[0,1]
	v_add_f32_e32 v0, v6, v0
	v_max_f32_e32 v12, 0, v12
	v_add_f32_e32 v0, v7, v0
	v_max_f32_e32 v13, 0, v13
	v_pk_mul_f32 v[12:13], v[138:139], v[12:13] op_sel:[1,0] op_sel_hi:[0,1]
	v_max_f32_e32 v14, 0, v14
	v_max_f32_e32 v15, 0, v15
	v_pk_mul_f32 v[14:15], v[140:141], v[14:15] op_sel:[1,0] op_sel_hi:[0,1]
	s_waitcnt lgkmcnt(0)
	ds_read_b128 v[244:247], v223
	ds_read_b128 v[104:107], v224
	v_add_f32_e32 v8, 0, v8
	v_add_f32_e32 v8, v9, v8
	v_add_f32_e32 v8, v10, v8
	v_add_f32_e32 v8, v11, v8
	v_max_f32_e32 v189, v189, v0
	v_min_f32_e32 v188, v188, v0
	v_add_f32_e32 v8, v12, v8
	v_add_f32_e32 v8, v13, v8
	v_add_f32_e32 v8, v14, v8
	v_add_f32_e32 v8, v15, v8
	s_waitcnt lgkmcnt(0)
	ds_write_b128 v222, v[236:239]
	ds_write_b128 v222, v[240:243] offset:1024
	ds_write2st64_b32 v196, v0, v8 offset1:64
	v_max_f32_e32 v16, 0, v16
	v_max_f32_e32 v17, 0, v17
	v_pk_mul_f32 v[16:17], v[142:143], v[16:17] op_sel:[1,0] op_sel_hi:[0,1]
	v_max_f32_e32 v187, v187, v8
	v_min_f32_e32 v186, v186, v8
	v_max_f32_e32 v18, 0, v18
	v_max_f32_e32 v19, 0, v19
	v_pk_mul_f32 v[18:19], v[144:145], v[18:19] op_sel:[1,0] op_sel_hi:[0,1]
	v_max_f32_e32 v20, 0, v20
	v_max_f32_e32 v21, 0, v21
	v_pk_mul_f32 v[20:21], v[146:147], v[20:21] op_sel:[1,0] op_sel_hi:[0,1]
	v_max_f32_e32 v22, 0, v22
	v_max_f32_e32 v23, 0, v23
	v_pk_mul_f32 v[22:23], v[148:149], v[22:23] op_sel:[1,0] op_sel_hi:[0,1]
	v_add_f32_e32 v16, 0, v16
	v_max_f32_e32 v24, 0, v24
	v_add_f32_e32 v16, v17, v16
	v_max_f32_e32 v25, 0, v25
	v_add_f32_e32 v16, v18, v16
	v_pk_mul_f32 v[24:25], v[150:151], v[24:25] op_sel:[1,0] op_sel_hi:[0,1]
	v_add_f32_e32 v16, v19, v16
	v_max_f32_e32 v26, 0, v26
	v_add_f32_e32 v16, v20, v16
	v_max_f32_e32 v27, 0, v27
	v_add_f32_e32 v16, v21, v16
	v_pk_mul_f32 v[26:27], v[152:153], v[26:27] op_sel:[1,0] op_sel_hi:[0,1]
	v_add_f32_e32 v16, v22, v16
	v_max_f32_e32 v28, 0, v28
	v_add_f32_e32 v16, v23, v16
	v_max_f32_e32 v29, 0, v29
	v_pk_mul_f32 v[28:29], v[154:155], v[28:29] op_sel:[1,0] op_sel_hi:[0,1]
	v_max_f32_e32 v30, 0, v30
	v_max_f32_e32 v31, 0, v31
	v_pk_mul_f32 v[30:31], v[156:157], v[30:31] op_sel:[1,0] op_sel_hi:[0,1]
	v_add_u32_e32 v3, 0x10000, v196
	s_waitcnt lgkmcnt(0)
	ds_read_b128 v[100:103], v223
	ds_read_b128 v[96:99], v224
	v_add_f32_e32 v24, 0, v24
	v_add_f32_e32 v24, v25, v24
	v_add_f32_e32 v24, v26, v24
	v_add_f32_e32 v24, v27, v24
	ds_write_b32 v3, v16
	v_max_f32_e32 v185, v185, v16
	v_min_f32_e32 v184, v184, v16
	v_add_f32_e32 v24, v28, v24
	v_add_f32_e32 v24, v29, v24
	v_add_f32_e32 v24, v30, v24
	v_add_f32_e32 v24, v31, v24
	v_add_u32_e32 v3, 0x14000, v196
	v_add_u32_e32 v196, 0x400, v196
	s_nop 0
	ds_write_b32 v3, v24
	v_max_f32_e32 v183, v183, v24
	v_min_f32_e32 v123, v123, v24
	s_mov_b32 s6, s3
	s_branch .Lidx_loopA
; #define LAS __attribute__((address_space(3)))
; __device__ __forceinline__ void indexer_phase(const bf16_t* PJ, float* rk, unsigned short* SEL, LAS unsigned char* lds) {
;     ...
;                 const int key = 32 * kt + r32;
; #pragma unroll
;                 for (int rt = 0; rt < 2; ++rt) {
;                     f32x16 acc = f32x16{};
; #pragma unroll
;                     for (int kk = 0; kk < 4; ++kk) acc = __builtin_amdgcn_mfma_f32_32x32x16_bf16(af[rt][kk], bcur[kk], acc, 0, 0, 0);
; #pragma unroll
;                     for (int qq = 0; qq < 2; ++qq) { float s = 0.f;
; #pragma unroll
;                         for (int e = 0; e < 8; ++e) s += wq[rt][qq][e] * fmaxf(acc[8 * qq + e], 0.f);
;                         ((LAS float*)lds)[(4 * rt + 2 * hi + qq) * 4096 + key] = s;
;                         const bool ok = key <= t0 + 4 * rt + 2 * hi + qq;
;                         rmax[rt][qq] = fmaxf(rmax[rt][qq], ok ? s : -INFINITY); rmin[rt][qq] = fminf(rmin[rt][qq], ok ? s : INFINITY); }
.Lidx_last:
	s_waitcnt lgkmcnt(0)
	v_mfma_f32_32x32x16_bf16 v[0:15], v[72:75], v[244:247], 0
	v_add_u32_e32 v197, s6, v110
	v_mfma_f32_32x32x16_bf16 v[0:15], v[64:67], v[104:107], v[0:15]
	v_mfma_f32_32x32x16_bf16 v[0:15], v[68:71], v[100:103], v[0:15]
	v_mfma_f32_32x32x16_bf16 v[0:15], v[76:79], v[96:99], v[0:15]
	v_mfma_f32_32x32x16_bf16 v[16:31], v[88:91], v[244:247], 0
	v_mfma_f32_32x32x16_bf16 v[16:31], v[80:83], v[104:107], v[16:31]
	v_mfma_f32_32x32x16_bf16 v[16:31], v[84:87], v[100:103], v[16:31]
	v_mfma_f32_32x32x16_bf16 v[16:31], v[92:95], v[96:99], v[16:31]
	s_nop 7
	v_max_f32_e32 v0, 0, v0
	v_max_f32_e32 v1, 0, v1
	v_pk_mul_f32 v[0:1], v[126:127], v[0:1] op_sel:[1,0] op_sel_hi:[0,1]
	v_max_f32_e32 v2, 0, v2
	v_max_f32_e32 v3, 0, v3
	v_pk_mul_f32 v[2:3], v[128:129], v[2:3] op_sel:[1,0] op_sel_hi:[0,1]
	v_max_f32_e32 v4, 0, v4
	v_max_f32_e32 v5, 0, v5
	v_pk_mul_f32 v[4:5], v[130:131], v[4:5] op_sel:[1,0] op_sel_hi:[0,1]
	v_max_f32_e32 v6, 0, v6
	v_max_f32_e32 v7, 0, v7
	v_pk_mul_f32 v[6:7], v[132:133], v[6:7] op_sel:[1,0] op_sel_hi:[0,1]
	v_add_f32_e32 v0, 0, v0
	v_max_f32_e32 v8, 0, v8
	v_add_f32_e32 v0, v1, v0
	v_max_f32_e32 v9, 0, v9
	v_add_f32_e32 v0, v2, v0
	v_pk_mul_f32 v[8:9], v[134:135], v[8:9] op_sel:[1,0] op_sel_hi:[0,1]
	v_add_f32_e32 v0, v3, v0
	v_max_f32_e32 v10, 0, v10
	v_add_f32_e32 v0, v4, v0
	v_max_f32_e32 v11, 0, v11
	v_add_f32_e32 v0, v5, v0
	v_pk_mul_f32 v[10:11], v[136:137], v[10:11] op_sel:[1,0] op_sel_hi:[0,1]
	v_add_f32_e32 v0, v6, v0
	v_max_f32_e32 v12, 0, v12
	v_add_f32_e32 v0, v7, v0
	v_max_f32_e32 v13, 0, v13
	v_pk_mul_f32 v[12:13], v[138:139], v[12:13] op_sel:[1,0] op_sel_hi:[0,1]
	v_max_f32_e32 v14, 0, v14
	v_max_f32_e32 v15, 0, v15
	v_pk_mul_f32 v[14:15], v[140:141], v[14:15] op_sel:[1,0] op_sel_hi:[0,1]
	v_cmp_gt_i32_e32 vcc, v197, v190
	v_add_f32_e32 v8, 0, v8
	v_add_f32_e32 v8, v9, v8
	v_add_f32_e32 v8, v10, v8
	v_add_f32_e32 v8, v11, v8
	v_cndmask_b32_e32 v1, v0, v178, vcc
	v_cndmask_b32_e32 v2, v0, v179, vcc
	v_max_f32_e32 v189, v189, v1
	v_min_f32_e32 v188, v188, v2
	v_add_f32_e32 v8, v12, v8
	v_add_f32_e32 v8, v13, v8
	v_add_f32_e32 v8, v14, v8
	v_add_f32_e32 v8, v15, v8
	v_cmp_gt_i32_e32 vcc, v197, v191
	ds_write2st64_b32 v196, v0, v8 offset1:64
	v_max_f32_e32 v16, 0, v16
	v_max_f32_e32 v17, 0, v17
	v_pk_mul_f32 v[16:17], v[142:143], v[16:17] op_sel:[1,0] op_sel_hi:[0,1]
	v_cndmask_b32_e32 v1, v8, v178, vcc
	v_cndmask_b32_e32 v2, v8, v179, vcc
	v_max_f32_e32 v187, v187, v1
	v_min_f32_e32 v186, v186, v2
	v_max_f32_e32 v18, 0, v18
	v_max_f32_e32 v19, 0, v19
	v_pk_mul_f32 v[18:19], v[144:145], v[18:19] op_sel:[1,0] op_sel_hi:[0,1]
	v_max_f32_e32 v20, 0, v20
	v_max_f32_e32 v21, 0, v21
	v_pk_mul_f32 v[20:21], v[146:147], v[20:21] op_sel:[1,0] op_sel_hi:[0,1]
	v_max_f32_e32 v22, 0, v22
	v_max_f32_e32 v23, 0, v23
	v_pk_mul_f32 v[22:23], v[148:149], v[22:23] op_sel:[1,0] op_sel_hi:[0,1]
	v_add_f32_e32 v16, 0, v16
	v_max_f32_e32 v24, 0, v24
	v_add_f32_e32 v16, v17, v16
	v_max_f32_e32 v25, 0, v25
	v_add_f32_e32 v16, v18, v16
	v_pk_mul_f32 v[24:25], v[150:151], v[24:25] op_sel:[1,0] op_sel_hi:[0,1]
	v_add_f32_e32 v16, v19, v16
	v_max_f32_e32 v26, 0, v26
	v_add_f32_e32 v16, v20, v16
	v_max_f32_e32 v27, 0, v27
	v_add_f32_e32 v16, v21, v16
	v_pk_mul_f32 v[26:27], v[152:153], v[26:27] op_sel:[1,0] op_sel_hi:[0,1]
	v_add_f32_e32 v16, v22, v16
	v_max_f32_e32 v28, 0, v28
	v_add_f32_e32 v16, v23, v16
	v_max_f32_e32 v29, 0, v29
	v_pk_mul_f32 v[28:29], v[154:155], v[28:29] op_sel:[1,0] op_sel_hi:[0,1]
	v_max_f32_e32 v30, 0, v30
	v_max_f32_e32 v31, 0, v31
	v_pk_mul_f32 v[30:31], v[156:157], v[30:31] op_sel:[1,0] op_sel_hi:[0,1]
	v_cmp_gt_i32_e32 vcc, v197, v192
	v_add_u32_e32 v3, 0x10000, v196
	v_add_f32_e32 v24, 0, v24
	v_add_f32_e32 v24, v25, v24
	v_add_f32_e32 v24, v26, v24
	v_add_f32_e32 v24, v27, v24
	ds_write_b32 v3, v16
	v_cndmask_b32_e32 v1, v16, v178, vcc
	v_cndmask_b32_e32 v2, v16, v179, vcc
	v_max_f32_e32 v185, v185, v1
	v_min_f32_e32 v184, v184, v2
	v_add_f32_e32 v24, v28, v24
	v_add_f32_e32 v24, v29, v24
	v_add_f32_e32 v24, v30, v24
	v_add_f32_e32 v24, v31, v24
	v_cmp_gt_i32_e32 vcc, v197, v193
	v_add_u32_e32 v3, 0x14000, v196
	v_add_u32_e32 v196, 0x400, v196
	s_nop 0
	ds_write_b32 v3, v24
	v_cndmask_b32_e32 v1, v24, v178, vcc
	v_cndmask_b32_e32 v2, v24, v179, vcc
	v_max_f32_e32 v183, v183, v1
	v_min_f32_e32 v123, v123, v2
	s_branch .LBB0_874
